# compress-bias: fully unrolled, three 16-row blocks (60 loads) in flight with counted waits; same fmac order
# speedup vs baseline: 1.0063x; 1.0063x over previous
.LBB0_23:
	global_load_dwordx4 v[24:27], v[12:13], off offset:32
	v_mov_b32_e32 v20, 0
	s_mov_b64 s[6:7], 0
	v_mov_b32_e32 v21, v19
	s_waitcnt vmcnt(0) lgkmcnt(0)
	v_lshl_add_u64 v[14:15], v[26:27], 0, v[8:9]
	v_lshl_add_u64 v[16:17], v[24:25], 0, v[10:11]
	s_mov_b64 s[100:101], 0x1000
	v_lshl_add_u64 v[56:57], v[14:15], 0, s[100:101]
	global_load_dword v112, v[14:15], off
	global_load_dword v113, v[14:15], off offset:512
	global_load_dword v114, v[14:15], off offset:1024
	global_load_dword v115, v[14:15], off offset:1536
	global_load_dword v116, v[14:15], off offset:2048
	global_load_dword v117, v[14:15], off offset:2560
	global_load_dword v118, v[14:15], off offset:3072
	global_load_dword v119, v[14:15], off offset:3584
	global_load_dword v120, v[56:57], off
	global_load_dword v121, v[56:57], off offset:512
	global_load_dword v122, v[56:57], off offset:1024
	global_load_dword v123, v[56:57], off offset:1536
	global_load_dword v124, v[56:57], off offset:2048
	global_load_dword v125, v[56:57], off offset:2560
	global_load_dword v126, v[56:57], off offset:3072
	global_load_dword v127, v[56:57], off offset:3584
	global_load_dwordx4 v[64:67], v[16:17], off
	global_load_dwordx4 v[68:71], v[16:17], off offset:16
	global_load_dwordx4 v[72:75], v[16:17], off offset:32
	global_load_dwordx4 v[76:79], v[16:17], off offset:48
	v_lshl_add_u64 v[14:15], v[56:57], 0, s[100:101]
	v_lshl_add_u64 v[16:17], v[16:17], 0, 64
	v_lshl_add_u64 v[56:57], v[14:15], 0, s[100:101]
	global_load_dword v128, v[14:15], off
	global_load_dword v129, v[14:15], off offset:512
	global_load_dword v130, v[14:15], off offset:1024
	global_load_dword v131, v[14:15], off offset:1536
	global_load_dword v132, v[14:15], off offset:2048
	global_load_dword v133, v[14:15], off offset:2560
	global_load_dword v134, v[14:15], off offset:3072
	global_load_dword v135, v[14:15], off offset:3584
	global_load_dword v136, v[56:57], off
	global_load_dword v137, v[56:57], off offset:512
	global_load_dword v138, v[56:57], off offset:1024
	global_load_dword v139, v[56:57], off offset:1536
	global_load_dword v140, v[56:57], off offset:2048
	global_load_dword v141, v[56:57], off offset:2560
	global_load_dword v142, v[56:57], off offset:3072
	global_load_dword v143, v[56:57], off offset:3584
	global_load_dwordx4 v[80:83], v[16:17], off
	global_load_dwordx4 v[84:87], v[16:17], off offset:16
	global_load_dwordx4 v[88:91], v[16:17], off offset:32
	global_load_dwordx4 v[92:95], v[16:17], off offset:48
	v_lshl_add_u64 v[14:15], v[56:57], 0, s[100:101]
	v_lshl_add_u64 v[16:17], v[16:17], 0, 64
	v_lshl_add_u64 v[56:57], v[14:15], 0, s[100:101]
	global_load_dword v144, v[14:15], off
	global_load_dword v145, v[14:15], off offset:512
	global_load_dword v146, v[14:15], off offset:1024
	global_load_dword v147, v[14:15], off offset:1536
	global_load_dword v148, v[14:15], off offset:2048
	global_load_dword v149, v[14:15], off offset:2560
	global_load_dword v150, v[14:15], off offset:3072
	global_load_dword v151, v[14:15], off offset:3584
	global_load_dword v152, v[56:57], off
	global_load_dword v153, v[56:57], off offset:512
	global_load_dword v154, v[56:57], off offset:1024
	global_load_dword v155, v[56:57], off offset:1536
	global_load_dword v156, v[56:57], off offset:2048
	global_load_dword v157, v[56:57], off offset:2560
	global_load_dword v158, v[56:57], off offset:3072
	global_load_dword v159, v[56:57], off offset:3584
	global_load_dwordx4 v[96:99], v[16:17], off
	global_load_dwordx4 v[100:103], v[16:17], off offset:16
	global_load_dwordx4 v[104:107], v[16:17], off offset:32
	global_load_dwordx4 v[108:111], v[16:17], off offset:48
	v_lshl_add_u64 v[14:15], v[56:57], 0, s[100:101]
	v_lshl_add_u64 v[16:17], v[16:17], 0, 64
	s_waitcnt vmcnt(40)
	v_fmac_f32_e32 v20, v64, v112
	v_fmac_f32_e32 v20, v65, v113
	v_fmac_f32_e32 v20, v66, v114
	v_fmac_f32_e32 v20, v67, v115
	v_fmac_f32_e32 v20, v68, v116
	v_fmac_f32_e32 v20, v69, v117
	v_fmac_f32_e32 v20, v70, v118
	v_fmac_f32_e32 v20, v71, v119
	v_fmac_f32_e32 v20, v72, v120
	v_fmac_f32_e32 v20, v73, v121
	v_fmac_f32_e32 v20, v74, v122
	v_fmac_f32_e32 v20, v75, v123
	v_fmac_f32_e32 v20, v76, v124
	v_fmac_f32_e32 v20, v77, v125
	v_fmac_f32_e32 v20, v78, v126
	v_fmac_f32_e32 v20, v79, v127
	v_lshl_add_u64 v[56:57], v[14:15], 0, s[100:101]
	global_load_dword v112, v[14:15], off
	global_load_dword v113, v[14:15], off offset:512
	global_load_dword v114, v[14:15], off offset:1024
	global_load_dword v115, v[14:15], off offset:1536
	global_load_dword v116, v[14:15], off offset:2048
	global_load_dword v117, v[14:15], off offset:2560
	global_load_dword v118, v[14:15], off offset:3072
	global_load_dword v119, v[14:15], off offset:3584
	global_load_dword v120, v[56:57], off
	global_load_dword v121, v[56:57], off offset:512
	global_load_dword v122, v[56:57], off offset:1024
	global_load_dword v123, v[56:57], off offset:1536
	global_load_dword v124, v[56:57], off offset:2048
	global_load_dword v125, v[56:57], off offset:2560
	global_load_dword v126, v[56:57], off offset:3072
	global_load_dword v127, v[56:57], off offset:3584
	global_load_dwordx4 v[64:67], v[16:17], off
	global_load_dwordx4 v[68:71], v[16:17], off offset:16
	global_load_dwordx4 v[72:75], v[16:17], off offset:32
	global_load_dwordx4 v[76:79], v[16:17], off offset:48
	v_lshl_add_u64 v[14:15], v[56:57], 0, s[100:101]
	v_lshl_add_u64 v[16:17], v[16:17], 0, 64
	s_waitcnt vmcnt(40)
	v_fmac_f32_e32 v20, v80, v128
	v_fmac_f32_e32 v20, v81, v129
	v_fmac_f32_e32 v20, v82, v130
	v_fmac_f32_e32 v20, v83, v131
	v_fmac_f32_e32 v20, v84, v132
	v_fmac_f32_e32 v20, v85, v133
	v_fmac_f32_e32 v20, v86, v134
	v_fmac_f32_e32 v20, v87, v135
	v_fmac_f32_e32 v20, v88, v136
	v_fmac_f32_e32 v20, v89, v137
	v_fmac_f32_e32 v20, v90, v138
	v_fmac_f32_e32 v20, v91, v139
	v_fmac_f32_e32 v20, v92, v140
	v_fmac_f32_e32 v20, v93, v141
	v_fmac_f32_e32 v20, v94, v142
	v_fmac_f32_e32 v20, v95, v143
	v_lshl_add_u64 v[56:57], v[14:15], 0, s[100:101]
	global_load_dword v128, v[14:15], off
	global_load_dword v129, v[14:15], off offset:512
	global_load_dword v130, v[14:15], off offset:1024
	global_load_dword v131, v[14:15], off offset:1536
	global_load_dword v132, v[14:15], off offset:2048
	global_load_dword v133, v[14:15], off offset:2560
	global_load_dword v134, v[14:15], off offset:3072
	global_load_dword v135, v[14:15], off offset:3584
	global_load_dword v136, v[56:57], off
	global_load_dword v137, v[56:57], off offset:512
	global_load_dword v138, v[56:57], off offset:1024
	global_load_dword v139, v[56:57], off offset:1536
	global_load_dword v140, v[56:57], off offset:2048
	global_load_dword v141, v[56:57], off offset:2560
	global_load_dword v142, v[56:57], off offset:3072
	global_load_dword v143, v[56:57], off offset:3584
	global_load_dwordx4 v[80:83], v[16:17], off
	global_load_dwordx4 v[84:87], v[16:17], off offset:16
	global_load_dwordx4 v[88:91], v[16:17], off offset:32
	global_load_dwordx4 v[92:95], v[16:17], off offset:48
	v_lshl_add_u64 v[14:15], v[56:57], 0, s[100:101]
	v_lshl_add_u64 v[16:17], v[16:17], 0, 64
	s_waitcnt vmcnt(40)
	v_fmac_f32_e32 v20, v96, v144
	v_fmac_f32_e32 v20, v97, v145
	v_fmac_f32_e32 v20, v98, v146
	v_fmac_f32_e32 v20, v99, v147
	v_fmac_f32_e32 v20, v100, v148
	v_fmac_f32_e32 v20, v101, v149
	v_fmac_f32_e32 v20, v102, v150
	v_fmac_f32_e32 v20, v103, v151
	v_fmac_f32_e32 v20, v104, v152
	v_fmac_f32_e32 v20, v105, v153
	v_fmac_f32_e32 v20, v106, v154
	v_fmac_f32_e32 v20, v107, v155
	v_fmac_f32_e32 v20, v108, v156
	v_fmac_f32_e32 v20, v109, v157
	v_fmac_f32_e32 v20, v110, v158
	v_fmac_f32_e32 v20, v111, v159
	v_lshl_add_u64 v[56:57], v[14:15], 0, s[100:101]
	global_load_dword v144, v[14:15], off
	global_load_dword v145, v[14:15], off offset:512
	global_load_dword v146, v[14:15], off offset:1024
	global_load_dword v147, v[14:15], off offset:1536
	global_load_dword v148, v[14:15], off offset:2048
	global_load_dword v149, v[14:15], off offset:2560
	global_load_dword v150, v[14:15], off offset:3072
	global_load_dword v151, v[14:15], off offset:3584
	global_load_dword v152, v[56:57], off
	global_load_dword v153, v[56:57], off offset:512
	global_load_dword v154, v[56:57], off offset:1024
	global_load_dword v155, v[56:57], off offset:1536
	global_load_dword v156, v[56:57], off offset:2048
	global_load_dword v157, v[56:57], off offset:2560
	global_load_dword v158, v[56:57], off offset:3072
	global_load_dword v159, v[56:57], off offset:3584
	global_load_dwordx4 v[96:99], v[16:17], off
	global_load_dwordx4 v[100:103], v[16:17], off offset:16
	global_load_dwordx4 v[104:107], v[16:17], off offset:32
	global_load_dwordx4 v[108:111], v[16:17], off offset:48
	v_lshl_add_u64 v[14:15], v[56:57], 0, s[100:101]
	v_lshl_add_u64 v[16:17], v[16:17], 0, 64
	s_waitcnt vmcnt(40)
	v_fmac_f32_e32 v20, v64, v112
	v_fmac_f32_e32 v20, v65, v113
	v_fmac_f32_e32 v20, v66, v114
	v_fmac_f32_e32 v20, v67, v115
	v_fmac_f32_e32 v20, v68, v116
	v_fmac_f32_e32 v20, v69, v117
	v_fmac_f32_e32 v20, v70, v118
	v_fmac_f32_e32 v20, v71, v119
	v_fmac_f32_e32 v20, v72, v120
	v_fmac_f32_e32 v20, v73, v121
	v_fmac_f32_e32 v20, v74, v122
	v_fmac_f32_e32 v20, v75, v123
	v_fmac_f32_e32 v20, v76, v124
	v_fmac_f32_e32 v20, v77, v125
	v_fmac_f32_e32 v20, v78, v126
	v_fmac_f32_e32 v20, v79, v127
	v_lshl_add_u64 v[56:57], v[14:15], 0, s[100:101]
	global_load_dword v112, v[14:15], off
	global_load_dword v113, v[14:15], off offset:512
	global_load_dword v114, v[14:15], off offset:1024
	global_load_dword v115, v[14:15], off offset:1536
	global_load_dword v116, v[14:15], off offset:2048
	global_load_dword v117, v[14:15], off offset:2560
	global_load_dword v118, v[14:15], off offset:3072
	global_load_dword v119, v[14:15], off offset:3584
	global_load_dword v120, v[56:57], off
	global_load_dword v121, v[56:57], off offset:512
	global_load_dword v122, v[56:57], off offset:1024
	global_load_dword v123, v[56:57], off offset:1536
	global_load_dword v124, v[56:57], off offset:2048
	global_load_dword v125, v[56:57], off offset:2560
	global_load_dword v126, v[56:57], off offset:3072
	global_load_dword v127, v[56:57], off offset:3584
	global_load_dwordx4 v[64:67], v[16:17], off
	global_load_dwordx4 v[68:71], v[16:17], off offset:16
	global_load_dwordx4 v[72:75], v[16:17], off offset:32
	global_load_dwordx4 v[76:79], v[16:17], off offset:48
	v_lshl_add_u64 v[14:15], v[56:57], 0, s[100:101]
	v_lshl_add_u64 v[16:17], v[16:17], 0, 64
	s_waitcnt vmcnt(40)
	v_fmac_f32_e32 v20, v80, v128
	v_fmac_f32_e32 v20, v81, v129
	v_fmac_f32_e32 v20, v82, v130
	v_fmac_f32_e32 v20, v83, v131
	v_fmac_f32_e32 v20, v84, v132
	v_fmac_f32_e32 v20, v85, v133
	v_fmac_f32_e32 v20, v86, v134
	v_fmac_f32_e32 v20, v87, v135
	v_fmac_f32_e32 v20, v88, v136
	v_fmac_f32_e32 v20, v89, v137
	v_fmac_f32_e32 v20, v90, v138
	v_fmac_f32_e32 v20, v91, v139
	v_fmac_f32_e32 v20, v92, v140
	v_fmac_f32_e32 v20, v93, v141
	v_fmac_f32_e32 v20, v94, v142
	v_fmac_f32_e32 v20, v95, v143
	v_lshl_add_u64 v[56:57], v[14:15], 0, s[100:101]
	global_load_dword v128, v[14:15], off
	global_load_dword v129, v[14:15], off offset:512
	global_load_dword v130, v[14:15], off offset:1024
	global_load_dword v131, v[14:15], off offset:1536
	global_load_dword v132, v[14:15], off offset:2048
	global_load_dword v133, v[14:15], off offset:2560
	global_load_dword v134, v[14:15], off offset:3072
	global_load_dword v135, v[14:15], off offset:3584
	global_load_dword v136, v[56:57], off
	global_load_dword v137, v[56:57], off offset:512
	global_load_dword v138, v[56:57], off offset:1024
	global_load_dword v139, v[56:57], off offset:1536
	global_load_dword v140, v[56:57], off offset:2048
	global_load_dword v141, v[56:57], off offset:2560
	global_load_dword v142, v[56:57], off offset:3072
	global_load_dword v143, v[56:57], off offset:3584
	global_load_dwordx4 v[80:83], v[16:17], off
	global_load_dwordx4 v[84:87], v[16:17], off offset:16
	global_load_dwordx4 v[88:91], v[16:17], off offset:32
	global_load_dwordx4 v[92:95], v[16:17], off offset:48
	v_lshl_add_u64 v[14:15], v[56:57], 0, s[100:101]
	v_lshl_add_u64 v[16:17], v[16:17], 0, 64
	s_waitcnt vmcnt(40)
	v_fmac_f32_e32 v20, v96, v144
	v_fmac_f32_e32 v20, v97, v145
	v_fmac_f32_e32 v20, v98, v146
	v_fmac_f32_e32 v20, v99, v147
	v_fmac_f32_e32 v20, v100, v148
	v_fmac_f32_e32 v20, v101, v149
	v_fmac_f32_e32 v20, v102, v150
	v_fmac_f32_e32 v20, v103, v151
	v_fmac_f32_e32 v20, v104, v152
	v_fmac_f32_e32 v20, v105, v153
	v_fmac_f32_e32 v20, v106, v154
	v_fmac_f32_e32 v20, v107, v155
	v_fmac_f32_e32 v20, v108, v156
	v_fmac_f32_e32 v20, v109, v157
	v_fmac_f32_e32 v20, v110, v158
	v_fmac_f32_e32 v20, v111, v159
	v_lshl_add_u64 v[56:57], v[14:15], 0, s[100:101]
	global_load_dword v144, v[14:15], off
	global_load_dword v145, v[14:15], off offset:512
	global_load_dword v146, v[14:15], off offset:1024
	global_load_dword v147, v[14:15], off offset:1536
	global_load_dword v148, v[14:15], off offset:2048
	global_load_dword v149, v[14:15], off offset:2560
	global_load_dword v150, v[14:15], off offset:3072
	global_load_dword v151, v[14:15], off offset:3584
	global_load_dword v152, v[56:57], off
	global_load_dword v153, v[56:57], off offset:512
	global_load_dword v154, v[56:57], off offset:1024
	global_load_dword v155, v[56:57], off offset:1536
	global_load_dword v156, v[56:57], off offset:2048
	global_load_dword v157, v[56:57], off offset:2560
	global_load_dword v158, v[56:57], off offset:3072
	global_load_dword v159, v[56:57], off offset:3584
	global_load_dwordx4 v[96:99], v[16:17], off
	global_load_dwordx4 v[100:103], v[16:17], off offset:16
	global_load_dwordx4 v[104:107], v[16:17], off offset:32
	global_load_dwordx4 v[108:111], v[16:17], off offset:48
	v_lshl_add_u64 v[14:15], v[56:57], 0, s[100:101]
	v_lshl_add_u64 v[16:17], v[16:17], 0, 64
	s_waitcnt vmcnt(40)
	v_fmac_f32_e32 v20, v64, v112
	v_fmac_f32_e32 v20, v65, v113
	v_fmac_f32_e32 v20, v66, v114
	v_fmac_f32_e32 v20, v67, v115
	v_fmac_f32_e32 v20, v68, v116
	v_fmac_f32_e32 v20, v69, v117
	v_fmac_f32_e32 v20, v70, v118
	v_fmac_f32_e32 v20, v71, v119
	v_fmac_f32_e32 v20, v72, v120
	v_fmac_f32_e32 v20, v73, v121
	v_fmac_f32_e32 v20, v74, v122
	v_fmac_f32_e32 v20, v75, v123
	v_fmac_f32_e32 v20, v76, v124
	v_fmac_f32_e32 v20, v77, v125
	v_fmac_f32_e32 v20, v78, v126
	v_fmac_f32_e32 v20, v79, v127
	v_lshl_add_u64 v[56:57], v[14:15], 0, s[100:101]
	global_load_dword v112, v[14:15], off
	global_load_dword v113, v[14:15], off offset:512
	global_load_dword v114, v[14:15], off offset:1024
	global_load_dword v115, v[14:15], off offset:1536
	global_load_dword v116, v[14:15], off offset:2048
	global_load_dword v117, v[14:15], off offset:2560
	global_load_dword v118, v[14:15], off offset:3072
	global_load_dword v119, v[14:15], off offset:3584
	global_load_dword v120, v[56:57], off
	global_load_dword v121, v[56:57], off offset:512
	global_load_dword v122, v[56:57], off offset:1024
	global_load_dword v123, v[56:57], off offset:1536
	global_load_dword v124, v[56:57], off offset:2048
	global_load_dword v125, v[56:57], off offset:2560
	global_load_dword v126, v[56:57], off offset:3072
	global_load_dword v127, v[56:57], off offset:3584
	global_load_dwordx4 v[64:67], v[16:17], off
	global_load_dwordx4 v[68:71], v[16:17], off offset:16
	global_load_dwordx4 v[72:75], v[16:17], off offset:32
	global_load_dwordx4 v[76:79], v[16:17], off offset:48
	v_lshl_add_u64 v[14:15], v[56:57], 0, s[100:101]
	v_lshl_add_u64 v[16:17], v[16:17], 0, 64
	s_waitcnt vmcnt(40)
	v_fmac_f32_e32 v20, v80, v128
	v_fmac_f32_e32 v20, v81, v129
	v_fmac_f32_e32 v20, v82, v130
	v_fmac_f32_e32 v20, v83, v131
	v_fmac_f32_e32 v20, v84, v132
	v_fmac_f32_e32 v20, v85, v133
	v_fmac_f32_e32 v20, v86, v134
	v_fmac_f32_e32 v20, v87, v135
	v_fmac_f32_e32 v20, v88, v136
	v_fmac_f32_e32 v20, v89, v137
	v_fmac_f32_e32 v20, v90, v138
	v_fmac_f32_e32 v20, v91, v139
	v_fmac_f32_e32 v20, v92, v140
	v_fmac_f32_e32 v20, v93, v141
	v_fmac_f32_e32 v20, v94, v142
	v_fmac_f32_e32 v20, v95, v143
	v_lshl_add_u64 v[56:57], v[14:15], 0, s[100:101]
	global_load_dword v128, v[14:15], off
	global_load_dword v129, v[14:15], off offset:512
	global_load_dword v130, v[14:15], off offset:1024
	global_load_dword v131, v[14:15], off offset:1536
	global_load_dword v132, v[14:15], off offset:2048
	global_load_dword v133, v[14:15], off offset:2560
	global_load_dword v134, v[14:15], off offset:3072
	global_load_dword v135, v[14:15], off offset:3584
	global_load_dword v136, v[56:57], off
	global_load_dword v137, v[56:57], off offset:512
	global_load_dword v138, v[56:57], off offset:1024
	global_load_dword v139, v[56:57], off offset:1536
	global_load_dword v140, v[56:57], off offset:2048
	global_load_dword v141, v[56:57], off offset:2560
	global_load_dword v142, v[56:57], off offset:3072
	global_load_dword v143, v[56:57], off offset:3584
	global_load_dwordx4 v[80:83], v[16:17], off
	global_load_dwordx4 v[84:87], v[16:17], off offset:16
	global_load_dwordx4 v[88:91], v[16:17], off offset:32
	global_load_dwordx4 v[92:95], v[16:17], off offset:48
	v_lshl_add_u64 v[14:15], v[56:57], 0, s[100:101]
	v_lshl_add_u64 v[16:17], v[16:17], 0, 64
	s_waitcnt vmcnt(40)
	v_fmac_f32_e32 v20, v96, v144
	v_fmac_f32_e32 v20, v97, v145
	v_fmac_f32_e32 v20, v98, v146
	v_fmac_f32_e32 v20, v99, v147
	v_fmac_f32_e32 v20, v100, v148
	v_fmac_f32_e32 v20, v101, v149
	v_fmac_f32_e32 v20, v102, v150
	v_fmac_f32_e32 v20, v103, v151
	v_fmac_f32_e32 v20, v104, v152
	v_fmac_f32_e32 v20, v105, v153
	v_fmac_f32_e32 v20, v106, v154
	v_fmac_f32_e32 v20, v107, v155
	v_fmac_f32_e32 v20, v108, v156
	v_fmac_f32_e32 v20, v109, v157
	v_fmac_f32_e32 v20, v110, v158
	v_fmac_f32_e32 v20, v111, v159
	v_lshl_add_u64 v[56:57], v[14:15], 0, s[100:101]
	global_load_dword v144, v[14:15], off
	global_load_dword v145, v[14:15], off offset:512
	global_load_dword v146, v[14:15], off offset:1024
	global_load_dword v147, v[14:15], off offset:1536
	global_load_dword v148, v[14:15], off offset:2048
	global_load_dword v149, v[14:15], off offset:2560
	global_load_dword v150, v[14:15], off offset:3072
	global_load_dword v151, v[14:15], off offset:3584
	global_load_dword v152, v[56:57], off
	global_load_dword v153, v[56:57], off offset:512
	global_load_dword v154, v[56:57], off offset:1024
	global_load_dword v155, v[56:57], off offset:1536
	global_load_dword v156, v[56:57], off offset:2048
	global_load_dword v157, v[56:57], off offset:2560
	global_load_dword v158, v[56:57], off offset:3072
	global_load_dword v159, v[56:57], off offset:3584
	global_load_dwordx4 v[96:99], v[16:17], off
	global_load_dwordx4 v[100:103], v[16:17], off offset:16
	global_load_dwordx4 v[104:107], v[16:17], off offset:32
	global_load_dwordx4 v[108:111], v[16:17], off offset:48
	v_lshl_add_u64 v[14:15], v[56:57], 0, s[100:101]
	v_lshl_add_u64 v[16:17], v[16:17], 0, 64
	s_waitcnt vmcnt(40)
	v_fmac_f32_e32 v20, v64, v112
	v_fmac_f32_e32 v20, v65, v113
	v_fmac_f32_e32 v20, v66, v114
	v_fmac_f32_e32 v20, v67, v115
	v_fmac_f32_e32 v20, v68, v116
	v_fmac_f32_e32 v20, v69, v117
	v_fmac_f32_e32 v20, v70, v118
	v_fmac_f32_e32 v20, v71, v119
	v_fmac_f32_e32 v20, v72, v120
	v_fmac_f32_e32 v20, v73, v121
	v_fmac_f32_e32 v20, v74, v122
	v_fmac_f32_e32 v20, v75, v123
	v_fmac_f32_e32 v20, v76, v124
	v_fmac_f32_e32 v20, v77, v125
	v_fmac_f32_e32 v20, v78, v126
	v_fmac_f32_e32 v20, v79, v127
	v_lshl_add_u64 v[56:57], v[14:15], 0, s[100:101]
	global_load_dword v112, v[14:15], off
	global_load_dword v113, v[14:15], off offset:512
	global_load_dword v114, v[14:15], off offset:1024
	global_load_dword v115, v[14:15], off offset:1536
	global_load_dword v116, v[14:15], off offset:2048
	global_load_dword v117, v[14:15], off offset:2560
	global_load_dword v118, v[14:15], off offset:3072
	global_load_dword v119, v[14:15], off offset:3584
	global_load_dword v120, v[56:57], off
	global_load_dword v121, v[56:57], off offset:512
	global_load_dword v122, v[56:57], off offset:1024
	global_load_dword v123, v[56:57], off offset:1536
	global_load_dword v124, v[56:57], off offset:2048
	global_load_dword v125, v[56:57], off offset:2560
	global_load_dword v126, v[56:57], off offset:3072
	global_load_dword v127, v[56:57], off offset:3584
	global_load_dwordx4 v[64:67], v[16:17], off
	global_load_dwordx4 v[68:71], v[16:17], off offset:16
	global_load_dwordx4 v[72:75], v[16:17], off offset:32
	global_load_dwordx4 v[76:79], v[16:17], off offset:48
	v_lshl_add_u64 v[14:15], v[56:57], 0, s[100:101]
	v_lshl_add_u64 v[16:17], v[16:17], 0, 64
	s_waitcnt vmcnt(40)
	v_fmac_f32_e32 v20, v80, v128
	v_fmac_f32_e32 v20, v81, v129
	v_fmac_f32_e32 v20, v82, v130
	v_fmac_f32_e32 v20, v83, v131
	v_fmac_f32_e32 v20, v84, v132
	v_fmac_f32_e32 v20, v85, v133
	v_fmac_f32_e32 v20, v86, v134
	v_fmac_f32_e32 v20, v87, v135
	v_fmac_f32_e32 v20, v88, v136
	v_fmac_f32_e32 v20, v89, v137
	v_fmac_f32_e32 v20, v90, v138
	v_fmac_f32_e32 v20, v91, v139
	v_fmac_f32_e32 v20, v92, v140
	v_fmac_f32_e32 v20, v93, v141
	v_fmac_f32_e32 v20, v94, v142
	v_fmac_f32_e32 v20, v95, v143
	v_lshl_add_u64 v[56:57], v[14:15], 0, s[100:101]
	global_load_dword v128, v[14:15], off
	global_load_dword v129, v[14:15], off offset:512
	global_load_dword v130, v[14:15], off offset:1024
	global_load_dword v131, v[14:15], off offset:1536
	global_load_dword v132, v[14:15], off offset:2048
	global_load_dword v133, v[14:15], off offset:2560
	global_load_dword v134, v[14:15], off offset:3072
	global_load_dword v135, v[14:15], off offset:3584
	global_load_dword v136, v[56:57], off
	global_load_dword v137, v[56:57], off offset:512
	global_load_dword v138, v[56:57], off offset:1024
	global_load_dword v139, v[56:57], off offset:1536
	global_load_dword v140, v[56:57], off offset:2048
	global_load_dword v141, v[56:57], off offset:2560
	global_load_dword v142, v[56:57], off offset:3072
	global_load_dword v143, v[56:57], off offset:3584
	global_load_dwordx4 v[80:83], v[16:17], off
	global_load_dwordx4 v[84:87], v[16:17], off offset:16
	global_load_dwordx4 v[88:91], v[16:17], off offset:32
	global_load_dwordx4 v[92:95], v[16:17], off offset:48
	v_lshl_add_u64 v[14:15], v[56:57], 0, s[100:101]
	v_lshl_add_u64 v[16:17], v[16:17], 0, 64
	s_waitcnt vmcnt(40)
	v_fmac_f32_e32 v20, v96, v144
	v_fmac_f32_e32 v20, v97, v145
	v_fmac_f32_e32 v20, v98, v146
	v_fmac_f32_e32 v20, v99, v147
	v_fmac_f32_e32 v20, v100, v148
	v_fmac_f32_e32 v20, v101, v149
	v_fmac_f32_e32 v20, v102, v150
	v_fmac_f32_e32 v20, v103, v151
	v_fmac_f32_e32 v20, v104, v152
	v_fmac_f32_e32 v20, v105, v153
	v_fmac_f32_e32 v20, v106, v154
	v_fmac_f32_e32 v20, v107, v155
	v_fmac_f32_e32 v20, v108, v156
	v_fmac_f32_e32 v20, v109, v157
	v_fmac_f32_e32 v20, v110, v158
	v_fmac_f32_e32 v20, v111, v159
	v_lshl_add_u64 v[56:57], v[14:15], 0, s[100:101]
	global_load_dword v144, v[14:15], off
	global_load_dword v145, v[14:15], off offset:512
	global_load_dword v146, v[14:15], off offset:1024
	global_load_dword v147, v[14:15], off offset:1536
	global_load_dword v148, v[14:15], off offset:2048
	global_load_dword v149, v[14:15], off offset:2560
	global_load_dword v150, v[14:15], off offset:3072
	global_load_dword v151, v[14:15], off offset:3584
	global_load_dword v152, v[56:57], off
	global_load_dword v153, v[56:57], off offset:512
	global_load_dword v154, v[56:57], off offset:1024
	global_load_dword v155, v[56:57], off offset:1536
	global_load_dword v156, v[56:57], off offset:2048
	global_load_dword v157, v[56:57], off offset:2560
	global_load_dword v158, v[56:57], off offset:3072
	global_load_dword v159, v[56:57], off offset:3584
	global_load_dwordx4 v[96:99], v[16:17], off
	global_load_dwordx4 v[100:103], v[16:17], off offset:16
	global_load_dwordx4 v[104:107], v[16:17], off offset:32
	global_load_dwordx4 v[108:111], v[16:17], off offset:48
	v_lshl_add_u64 v[14:15], v[56:57], 0, s[100:101]
	v_lshl_add_u64 v[16:17], v[16:17], 0, 64
	s_waitcnt vmcnt(40)
	v_fmac_f32_e32 v20, v64, v112
	v_fmac_f32_e32 v20, v65, v113
	v_fmac_f32_e32 v20, v66, v114
	v_fmac_f32_e32 v20, v67, v115
	v_fmac_f32_e32 v20, v68, v116
	v_fmac_f32_e32 v20, v69, v117
	v_fmac_f32_e32 v20, v70, v118
	v_fmac_f32_e32 v20, v71, v119
	v_fmac_f32_e32 v20, v72, v120
	v_fmac_f32_e32 v20, v73, v121
	v_fmac_f32_e32 v20, v74, v122
	v_fmac_f32_e32 v20, v75, v123
	v_fmac_f32_e32 v20, v76, v124
	v_fmac_f32_e32 v20, v77, v125
	v_fmac_f32_e32 v20, v78, v126
	v_fmac_f32_e32 v20, v79, v127
	v_lshl_add_u64 v[56:57], v[14:15], 0, s[100:101]
	global_load_dword v112, v[14:15], off
	global_load_dword v113, v[14:15], off offset:512
	global_load_dword v114, v[14:15], off offset:1024
	global_load_dword v115, v[14:15], off offset:1536
	global_load_dword v116, v[14:15], off offset:2048
	global_load_dword v117, v[14:15], off offset:2560
	global_load_dword v118, v[14:15], off offset:3072
	global_load_dword v119, v[14:15], off offset:3584
	global_load_dword v120, v[56:57], off
	global_load_dword v121, v[56:57], off offset:512
	global_load_dword v122, v[56:57], off offset:1024
	global_load_dword v123, v[56:57], off offset:1536
	global_load_dword v124, v[56:57], off offset:2048
	global_load_dword v125, v[56:57], off offset:2560
	global_load_dword v126, v[56:57], off offset:3072
	global_load_dword v127, v[56:57], off offset:3584
	global_load_dwordx4 v[64:67], v[16:17], off
	global_load_dwordx4 v[68:71], v[16:17], off offset:16
	global_load_dwordx4 v[72:75], v[16:17], off offset:32
	global_load_dwordx4 v[76:79], v[16:17], off offset:48
	v_lshl_add_u64 v[14:15], v[56:57], 0, s[100:101]
	v_lshl_add_u64 v[16:17], v[16:17], 0, 64
	s_waitcnt vmcnt(40)
	v_fmac_f32_e32 v20, v80, v128
	v_fmac_f32_e32 v20, v81, v129
	v_fmac_f32_e32 v20, v82, v130
	v_fmac_f32_e32 v20, v83, v131
	v_fmac_f32_e32 v20, v84, v132
	v_fmac_f32_e32 v20, v85, v133
	v_fmac_f32_e32 v20, v86, v134
	v_fmac_f32_e32 v20, v87, v135
	v_fmac_f32_e32 v20, v88, v136
	v_fmac_f32_e32 v20, v89, v137
	v_fmac_f32_e32 v20, v90, v138
	v_fmac_f32_e32 v20, v91, v139
	v_fmac_f32_e32 v20, v92, v140
	v_fmac_f32_e32 v20, v93, v141
	v_fmac_f32_e32 v20, v94, v142
	v_fmac_f32_e32 v20, v95, v143
	v_lshl_add_u64 v[56:57], v[14:15], 0, s[100:101]
	global_load_dword v128, v[14:15], off
	global_load_dword v129, v[14:15], off offset:512
	global_load_dword v130, v[14:15], off offset:1024
	global_load_dword v131, v[14:15], off offset:1536
	global_load_dword v132, v[14:15], off offset:2048
	global_load_dword v133, v[14:15], off offset:2560
	global_load_dword v134, v[14:15], off offset:3072
	global_load_dword v135, v[14:15], off offset:3584
	global_load_dword v136, v[56:57], off
	global_load_dword v137, v[56:57], off offset:512
	global_load_dword v138, v[56:57], off offset:1024
	global_load_dword v139, v[56:57], off offset:1536
	global_load_dword v140, v[56:57], off offset:2048
	global_load_dword v141, v[56:57], off offset:2560
	global_load_dword v142, v[56:57], off offset:3072
	global_load_dword v143, v[56:57], off offset:3584
	global_load_dwordx4 v[80:83], v[16:17], off
	global_load_dwordx4 v[84:87], v[16:17], off offset:16
	global_load_dwordx4 v[88:91], v[16:17], off offset:32
	global_load_dwordx4 v[92:95], v[16:17], off offset:48
	v_lshl_add_u64 v[14:15], v[56:57], 0, s[100:101]
	v_lshl_add_u64 v[16:17], v[16:17], 0, 64
	s_waitcnt vmcnt(40)
	v_fmac_f32_e32 v20, v96, v144
	v_fmac_f32_e32 v20, v97, v145
	v_fmac_f32_e32 v20, v98, v146
	v_fmac_f32_e32 v20, v99, v147
	v_fmac_f32_e32 v20, v100, v148
	v_fmac_f32_e32 v20, v101, v149
	v_fmac_f32_e32 v20, v102, v150
	v_fmac_f32_e32 v20, v103, v151
	v_fmac_f32_e32 v20, v104, v152
	v_fmac_f32_e32 v20, v105, v153
	v_fmac_f32_e32 v20, v106, v154
	v_fmac_f32_e32 v20, v107, v155
	v_fmac_f32_e32 v20, v108, v156
	v_fmac_f32_e32 v20, v109, v157
	v_fmac_f32_e32 v20, v110, v158
	v_fmac_f32_e32 v20, v111, v159
	v_lshl_add_u64 v[56:57], v[14:15], 0, s[100:101]
	global_load_dword v144, v[14:15], off
	global_load_dword v145, v[14:15], off offset:512
	global_load_dword v146, v[14:15], off offset:1024
	global_load_dword v147, v[14:15], off offset:1536
	global_load_dword v148, v[14:15], off offset:2048
	global_load_dword v149, v[14:15], off offset:2560
	global_load_dword v150, v[14:15], off offset:3072
	global_load_dword v151, v[14:15], off offset:3584
	global_load_dword v152, v[56:57], off
	global_load_dword v153, v[56:57], off offset:512
	global_load_dword v154, v[56:57], off offset:1024
	global_load_dword v155, v[56:57], off offset:1536
	global_load_dword v156, v[56:57], off offset:2048
	global_load_dword v157, v[56:57], off offset:2560
	global_load_dword v158, v[56:57], off offset:3072
	global_load_dword v159, v[56:57], off offset:3584
	global_load_dwordx4 v[96:99], v[16:17], off
	global_load_dwordx4 v[100:103], v[16:17], off offset:16
	global_load_dwordx4 v[104:107], v[16:17], off offset:32
	global_load_dwordx4 v[108:111], v[16:17], off offset:48
	v_lshl_add_u64 v[14:15], v[56:57], 0, s[100:101]
	v_lshl_add_u64 v[16:17], v[16:17], 0, 64
	s_waitcnt vmcnt(40)
	v_fmac_f32_e32 v20, v64, v112
	v_fmac_f32_e32 v20, v65, v113
	v_fmac_f32_e32 v20, v66, v114
	v_fmac_f32_e32 v20, v67, v115
	v_fmac_f32_e32 v20, v68, v116
	v_fmac_f32_e32 v20, v69, v117
	v_fmac_f32_e32 v20, v70, v118
	v_fmac_f32_e32 v20, v71, v119
	v_fmac_f32_e32 v20, v72, v120
	v_fmac_f32_e32 v20, v73, v121
	v_fmac_f32_e32 v20, v74, v122
	v_fmac_f32_e32 v20, v75, v123
	v_fmac_f32_e32 v20, v76, v124
	v_fmac_f32_e32 v20, v77, v125
	v_fmac_f32_e32 v20, v78, v126
	v_fmac_f32_e32 v20, v79, v127
	v_lshl_add_u64 v[56:57], v[14:15], 0, s[100:101]
	global_load_dword v112, v[14:15], off
	global_load_dword v113, v[14:15], off offset:512
	global_load_dword v114, v[14:15], off offset:1024
	global_load_dword v115, v[14:15], off offset:1536
	global_load_dword v116, v[14:15], off offset:2048
	global_load_dword v117, v[14:15], off offset:2560
	global_load_dword v118, v[14:15], off offset:3072
	global_load_dword v119, v[14:15], off offset:3584
	global_load_dword v120, v[56:57], off
	global_load_dword v121, v[56:57], off offset:512
	global_load_dword v122, v[56:57], off offset:1024
	global_load_dword v123, v[56:57], off offset:1536
	global_load_dword v124, v[56:57], off offset:2048
	global_load_dword v125, v[56:57], off offset:2560
	global_load_dword v126, v[56:57], off offset:3072
	global_load_dword v127, v[56:57], off offset:3584
	global_load_dwordx4 v[64:67], v[16:17], off
	global_load_dwordx4 v[68:71], v[16:17], off offset:16
	global_load_dwordx4 v[72:75], v[16:17], off offset:32
	global_load_dwordx4 v[76:79], v[16:17], off offset:48
	v_lshl_add_u64 v[14:15], v[56:57], 0, s[100:101]
	v_lshl_add_u64 v[16:17], v[16:17], 0, 64
	s_waitcnt vmcnt(40)
	v_fmac_f32_e32 v20, v80, v128
	v_fmac_f32_e32 v20, v81, v129
	v_fmac_f32_e32 v20, v82, v130
	v_fmac_f32_e32 v20, v83, v131
	v_fmac_f32_e32 v20, v84, v132
	v_fmac_f32_e32 v20, v85, v133
	v_fmac_f32_e32 v20, v86, v134
	v_fmac_f32_e32 v20, v87, v135
	v_fmac_f32_e32 v20, v88, v136
	v_fmac_f32_e32 v20, v89, v137
	v_fmac_f32_e32 v20, v90, v138
	v_fmac_f32_e32 v20, v91, v139
	v_fmac_f32_e32 v20, v92, v140
	v_fmac_f32_e32 v20, v93, v141
	v_fmac_f32_e32 v20, v94, v142
	v_fmac_f32_e32 v20, v95, v143
	v_lshl_add_u64 v[56:57], v[14:15], 0, s[100:101]
	global_load_dword v128, v[14:15], off
	global_load_dword v129, v[14:15], off offset:512
	global_load_dword v130, v[14:15], off offset:1024
	global_load_dword v131, v[14:15], off offset:1536
	global_load_dword v132, v[14:15], off offset:2048
	global_load_dword v133, v[14:15], off offset:2560
	global_load_dword v134, v[14:15], off offset:3072
	global_load_dword v135, v[14:15], off offset:3584
	global_load_dword v136, v[56:57], off
	global_load_dword v137, v[56:57], off offset:512
	global_load_dword v138, v[56:57], off offset:1024
	global_load_dword v139, v[56:57], off offset:1536
	global_load_dword v140, v[56:57], off offset:2048
	global_load_dword v141, v[56:57], off offset:2560
	global_load_dword v142, v[56:57], off offset:3072
	global_load_dword v143, v[56:57], off offset:3584
	global_load_dwordx4 v[80:83], v[16:17], off
	global_load_dwordx4 v[84:87], v[16:17], off offset:16
	global_load_dwordx4 v[88:91], v[16:17], off offset:32
	global_load_dwordx4 v[92:95], v[16:17], off offset:48
	v_lshl_add_u64 v[14:15], v[56:57], 0, s[100:101]
	v_lshl_add_u64 v[16:17], v[16:17], 0, 64
	s_waitcnt vmcnt(40)
	v_fmac_f32_e32 v20, v96, v144
	v_fmac_f32_e32 v20, v97, v145
	v_fmac_f32_e32 v20, v98, v146
	v_fmac_f32_e32 v20, v99, v147
	v_fmac_f32_e32 v20, v100, v148
	v_fmac_f32_e32 v20, v101, v149
	v_fmac_f32_e32 v20, v102, v150
	v_fmac_f32_e32 v20, v103, v151
	v_fmac_f32_e32 v20, v104, v152
	v_fmac_f32_e32 v20, v105, v153
	v_fmac_f32_e32 v20, v106, v154
	v_fmac_f32_e32 v20, v107, v155
	v_fmac_f32_e32 v20, v108, v156
	v_fmac_f32_e32 v20, v109, v157
	v_fmac_f32_e32 v20, v110, v158
	v_fmac_f32_e32 v20, v111, v159
	v_lshl_add_u64 v[56:57], v[14:15], 0, s[100:101]
	global_load_dword v144, v[14:15], off
	global_load_dword v145, v[14:15], off offset:512
	global_load_dword v146, v[14:15], off offset:1024
	global_load_dword v147, v[14:15], off offset:1536
	global_load_dword v148, v[14:15], off offset:2048
	global_load_dword v149, v[14:15], off offset:2560
	global_load_dword v150, v[14:15], off offset:3072
	global_load_dword v151, v[14:15], off offset:3584
	global_load_dword v152, v[56:57], off
	global_load_dword v153, v[56:57], off offset:512
	global_load_dword v154, v[56:57], off offset:1024
	global_load_dword v155, v[56:57], off offset:1536
	global_load_dword v156, v[56:57], off offset:2048
	global_load_dword v157, v[56:57], off offset:2560
	global_load_dword v158, v[56:57], off offset:3072
	global_load_dword v159, v[56:57], off offset:3584
	global_load_dwordx4 v[96:99], v[16:17], off
	global_load_dwordx4 v[100:103], v[16:17], off offset:16
	global_load_dwordx4 v[104:107], v[16:17], off offset:32
	global_load_dwordx4 v[108:111], v[16:17], off offset:48
	v_lshl_add_u64 v[14:15], v[56:57], 0, s[100:101]
	v_lshl_add_u64 v[16:17], v[16:17], 0, 64
	s_waitcnt vmcnt(40)
	v_fmac_f32_e32 v20, v64, v112
	v_fmac_f32_e32 v20, v65, v113
	v_fmac_f32_e32 v20, v66, v114
	v_fmac_f32_e32 v20, v67, v115
	v_fmac_f32_e32 v20, v68, v116
	v_fmac_f32_e32 v20, v69, v117
	v_fmac_f32_e32 v20, v70, v118
	v_fmac_f32_e32 v20, v71, v119
	v_fmac_f32_e32 v20, v72, v120
	v_fmac_f32_e32 v20, v73, v121
	v_fmac_f32_e32 v20, v74, v122
	v_fmac_f32_e32 v20, v75, v123
	v_fmac_f32_e32 v20, v76, v124
	v_fmac_f32_e32 v20, v77, v125
	v_fmac_f32_e32 v20, v78, v126
	v_fmac_f32_e32 v20, v79, v127
	v_lshl_add_u64 v[56:57], v[14:15], 0, s[100:101]
	global_load_dword v112, v[14:15], off
	global_load_dword v113, v[14:15], off offset:512
	global_load_dword v114, v[14:15], off offset:1024
	global_load_dword v115, v[14:15], off offset:1536
	global_load_dword v116, v[14:15], off offset:2048
	global_load_dword v117, v[14:15], off offset:2560
	global_load_dword v118, v[14:15], off offset:3072
	global_load_dword v119, v[14:15], off offset:3584
	global_load_dword v120, v[56:57], off
	global_load_dword v121, v[56:57], off offset:512
	global_load_dword v122, v[56:57], off offset:1024
	global_load_dword v123, v[56:57], off offset:1536
	global_load_dword v124, v[56:57], off offset:2048
	global_load_dword v125, v[56:57], off offset:2560
	global_load_dword v126, v[56:57], off offset:3072
	global_load_dword v127, v[56:57], off offset:3584
	global_load_dwordx4 v[64:67], v[16:17], off
	global_load_dwordx4 v[68:71], v[16:17], off offset:16
	global_load_dwordx4 v[72:75], v[16:17], off offset:32
	global_load_dwordx4 v[76:79], v[16:17], off offset:48
	v_lshl_add_u64 v[14:15], v[56:57], 0, s[100:101]
	v_lshl_add_u64 v[16:17], v[16:17], 0, 64
	s_waitcnt vmcnt(40)
	v_fmac_f32_e32 v20, v80, v128
	v_fmac_f32_e32 v20, v81, v129
	v_fmac_f32_e32 v20, v82, v130
	v_fmac_f32_e32 v20, v83, v131
	v_fmac_f32_e32 v20, v84, v132
	v_fmac_f32_e32 v20, v85, v133
	v_fmac_f32_e32 v20, v86, v134
	v_fmac_f32_e32 v20, v87, v135
	v_fmac_f32_e32 v20, v88, v136
	v_fmac_f32_e32 v20, v89, v137
	v_fmac_f32_e32 v20, v90, v138
	v_fmac_f32_e32 v20, v91, v139
	v_fmac_f32_e32 v20, v92, v140
	v_fmac_f32_e32 v20, v93, v141
	v_fmac_f32_e32 v20, v94, v142
	v_fmac_f32_e32 v20, v95, v143
	v_lshl_add_u64 v[56:57], v[14:15], 0, s[100:101]
	global_load_dword v128, v[14:15], off
	global_load_dword v129, v[14:15], off offset:512
	global_load_dword v130, v[14:15], off offset:1024
	global_load_dword v131, v[14:15], off offset:1536
	global_load_dword v132, v[14:15], off offset:2048
	global_load_dword v133, v[14:15], off offset:2560
	global_load_dword v134, v[14:15], off offset:3072
	global_load_dword v135, v[14:15], off offset:3584
	global_load_dword v136, v[56:57], off
	global_load_dword v137, v[56:57], off offset:512
	global_load_dword v138, v[56:57], off offset:1024
	global_load_dword v139, v[56:57], off offset:1536
	global_load_dword v140, v[56:57], off offset:2048
	global_load_dword v141, v[56:57], off offset:2560
	global_load_dword v142, v[56:57], off offset:3072
	global_load_dword v143, v[56:57], off offset:3584
	global_load_dwordx4 v[80:83], v[16:17], off
	global_load_dwordx4 v[84:87], v[16:17], off offset:16
	global_load_dwordx4 v[88:91], v[16:17], off offset:32
	global_load_dwordx4 v[92:95], v[16:17], off offset:48
	v_lshl_add_u64 v[14:15], v[56:57], 0, s[100:101]
	v_lshl_add_u64 v[16:17], v[16:17], 0, 64
	s_waitcnt vmcnt(40)
	v_fmac_f32_e32 v20, v96, v144
	v_fmac_f32_e32 v20, v97, v145
	v_fmac_f32_e32 v20, v98, v146
	v_fmac_f32_e32 v20, v99, v147
	v_fmac_f32_e32 v20, v100, v148
	v_fmac_f32_e32 v20, v101, v149
	v_fmac_f32_e32 v20, v102, v150
	v_fmac_f32_e32 v20, v103, v151
	v_fmac_f32_e32 v20, v104, v152
	v_fmac_f32_e32 v20, v105, v153
	v_fmac_f32_e32 v20, v106, v154
	v_fmac_f32_e32 v20, v107, v155
	v_fmac_f32_e32 v20, v108, v156
	v_fmac_f32_e32 v20, v109, v157
	v_fmac_f32_e32 v20, v110, v158
	v_fmac_f32_e32 v20, v111, v159
	v_lshl_add_u64 v[56:57], v[14:15], 0, s[100:101]
	global_load_dword v144, v[14:15], off
	global_load_dword v145, v[14:15], off offset:512
	global_load_dword v146, v[14:15], off offset:1024
	global_load_dword v147, v[14:15], off offset:1536
	global_load_dword v148, v[14:15], off offset:2048
	global_load_dword v149, v[14:15], off offset:2560
	global_load_dword v150, v[14:15], off offset:3072
	global_load_dword v151, v[14:15], off offset:3584
	global_load_dword v152, v[56:57], off
	global_load_dword v153, v[56:57], off offset:512
	global_load_dword v154, v[56:57], off offset:1024
	global_load_dword v155, v[56:57], off offset:1536
	global_load_dword v156, v[56:57], off offset:2048
	global_load_dword v157, v[56:57], off offset:2560
	global_load_dword v158, v[56:57], off offset:3072
	global_load_dword v159, v[56:57], off offset:3584
	global_load_dwordx4 v[96:99], v[16:17], off
	global_load_dwordx4 v[100:103], v[16:17], off offset:16
	global_load_dwordx4 v[104:107], v[16:17], off offset:32
	global_load_dwordx4 v[108:111], v[16:17], off offset:48
	v_lshl_add_u64 v[14:15], v[56:57], 0, s[100:101]
	v_lshl_add_u64 v[16:17], v[16:17], 0, 64
	s_waitcnt vmcnt(40)
	v_fmac_f32_e32 v20, v64, v112
	v_fmac_f32_e32 v20, v65, v113
	v_fmac_f32_e32 v20, v66, v114
	v_fmac_f32_e32 v20, v67, v115
	v_fmac_f32_e32 v20, v68, v116
	v_fmac_f32_e32 v20, v69, v117
	v_fmac_f32_e32 v20, v70, v118
	v_fmac_f32_e32 v20, v71, v119
	v_fmac_f32_e32 v20, v72, v120
	v_fmac_f32_e32 v20, v73, v121
	v_fmac_f32_e32 v20, v74, v122
	v_fmac_f32_e32 v20, v75, v123
	v_fmac_f32_e32 v20, v76, v124
	v_fmac_f32_e32 v20, v77, v125
	v_fmac_f32_e32 v20, v78, v126
	v_fmac_f32_e32 v20, v79, v127
	v_lshl_add_u64 v[56:57], v[14:15], 0, s[100:101]
	global_load_dword v112, v[14:15], off
	global_load_dword v113, v[14:15], off offset:512
	global_load_dword v114, v[14:15], off offset:1024
	global_load_dword v115, v[14:15], off offset:1536
	global_load_dword v116, v[14:15], off offset:2048
	global_load_dword v117, v[14:15], off offset:2560
	global_load_dword v118, v[14:15], off offset:3072
	global_load_dword v119, v[14:15], off offset:3584
	global_load_dword v120, v[56:57], off
	global_load_dword v121, v[56:57], off offset:512
	global_load_dword v122, v[56:57], off offset:1024
	global_load_dword v123, v[56:57], off offset:1536
	global_load_dword v124, v[56:57], off offset:2048
	global_load_dword v125, v[56:57], off offset:2560
	global_load_dword v126, v[56:57], off offset:3072
	global_load_dword v127, v[56:57], off offset:3584
	global_load_dwordx4 v[64:67], v[16:17], off
	global_load_dwordx4 v[68:71], v[16:17], off offset:16
	global_load_dwordx4 v[72:75], v[16:17], off offset:32
	global_load_dwordx4 v[76:79], v[16:17], off offset:48
	v_lshl_add_u64 v[14:15], v[56:57], 0, s[100:101]
	v_lshl_add_u64 v[16:17], v[16:17], 0, 64
	s_waitcnt vmcnt(40)
	v_fmac_f32_e32 v20, v80, v128
	v_fmac_f32_e32 v20, v81, v129
	v_fmac_f32_e32 v20, v82, v130
	v_fmac_f32_e32 v20, v83, v131
	v_fmac_f32_e32 v20, v84, v132
	v_fmac_f32_e32 v20, v85, v133
	v_fmac_f32_e32 v20, v86, v134
	v_fmac_f32_e32 v20, v87, v135
	v_fmac_f32_e32 v20, v88, v136
	v_fmac_f32_e32 v20, v89, v137
	v_fmac_f32_e32 v20, v90, v138
	v_fmac_f32_e32 v20, v91, v139
	v_fmac_f32_e32 v20, v92, v140
	v_fmac_f32_e32 v20, v93, v141
	v_fmac_f32_e32 v20, v94, v142
	v_fmac_f32_e32 v20, v95, v143
	v_lshl_add_u64 v[56:57], v[14:15], 0, s[100:101]
	global_load_dword v128, v[14:15], off
	global_load_dword v129, v[14:15], off offset:512
	global_load_dword v130, v[14:15], off offset:1024
	global_load_dword v131, v[14:15], off offset:1536
	global_load_dword v132, v[14:15], off offset:2048
	global_load_dword v133, v[14:15], off offset:2560
	global_load_dword v134, v[14:15], off offset:3072
	global_load_dword v135, v[14:15], off offset:3584
	global_load_dword v136, v[56:57], off
	global_load_dword v137, v[56:57], off offset:512
	global_load_dword v138, v[56:57], off offset:1024
	global_load_dword v139, v[56:57], off offset:1536
	global_load_dword v140, v[56:57], off offset:2048
	global_load_dword v141, v[56:57], off offset:2560
	global_load_dword v142, v[56:57], off offset:3072
	global_load_dword v143, v[56:57], off offset:3584
	global_load_dwordx4 v[80:83], v[16:17], off
	global_load_dwordx4 v[84:87], v[16:17], off offset:16
	global_load_dwordx4 v[88:91], v[16:17], off offset:32
	global_load_dwordx4 v[92:95], v[16:17], off offset:48
	v_lshl_add_u64 v[14:15], v[56:57], 0, s[100:101]
	v_lshl_add_u64 v[16:17], v[16:17], 0, 64
	s_waitcnt vmcnt(40)
	v_fmac_f32_e32 v20, v96, v144
	v_fmac_f32_e32 v20, v97, v145
	v_fmac_f32_e32 v20, v98, v146
	v_fmac_f32_e32 v20, v99, v147
	v_fmac_f32_e32 v20, v100, v148
	v_fmac_f32_e32 v20, v101, v149
	v_fmac_f32_e32 v20, v102, v150
	v_fmac_f32_e32 v20, v103, v151
	v_fmac_f32_e32 v20, v104, v152
	v_fmac_f32_e32 v20, v105, v153
	v_fmac_f32_e32 v20, v106, v154
	v_fmac_f32_e32 v20, v107, v155
	v_fmac_f32_e32 v20, v108, v156
	v_fmac_f32_e32 v20, v109, v157
	v_fmac_f32_e32 v20, v110, v158
	v_fmac_f32_e32 v20, v111, v159
	v_lshl_add_u64 v[56:57], v[14:15], 0, s[100:101]
	global_load_dword v144, v[14:15], off
	global_load_dword v145, v[14:15], off offset:512
	global_load_dword v146, v[14:15], off offset:1024
	global_load_dword v147, v[14:15], off offset:1536
	global_load_dword v148, v[14:15], off offset:2048
	global_load_dword v149, v[14:15], off offset:2560
	global_load_dword v150, v[14:15], off offset:3072
	global_load_dword v151, v[14:15], off offset:3584
	global_load_dword v152, v[56:57], off
	global_load_dword v153, v[56:57], off offset:512
	global_load_dword v154, v[56:57], off offset:1024
	global_load_dword v155, v[56:57], off offset:1536
	global_load_dword v156, v[56:57], off offset:2048
	global_load_dword v157, v[56:57], off offset:2560
	global_load_dword v158, v[56:57], off offset:3072
	global_load_dword v159, v[56:57], off offset:3584
	global_load_dwordx4 v[96:99], v[16:17], off
	global_load_dwordx4 v[100:103], v[16:17], off offset:16
	global_load_dwordx4 v[104:107], v[16:17], off offset:32
	global_load_dwordx4 v[108:111], v[16:17], off offset:48
	v_lshl_add_u64 v[14:15], v[56:57], 0, s[100:101]
	v_lshl_add_u64 v[16:17], v[16:17], 0, 64
	s_waitcnt vmcnt(40)
	v_fmac_f32_e32 v20, v64, v112
	v_fmac_f32_e32 v20, v65, v113
	v_fmac_f32_e32 v20, v66, v114
	v_fmac_f32_e32 v20, v67, v115
	v_fmac_f32_e32 v20, v68, v116
	v_fmac_f32_e32 v20, v69, v117
	v_fmac_f32_e32 v20, v70, v118
	v_fmac_f32_e32 v20, v71, v119
	v_fmac_f32_e32 v20, v72, v120
	v_fmac_f32_e32 v20, v73, v121
	v_fmac_f32_e32 v20, v74, v122
	v_fmac_f32_e32 v20, v75, v123
	v_fmac_f32_e32 v20, v76, v124
	v_fmac_f32_e32 v20, v77, v125
	v_fmac_f32_e32 v20, v78, v126
	v_fmac_f32_e32 v20, v79, v127
	v_lshl_add_u64 v[56:57], v[14:15], 0, s[100:101]
	global_load_dword v112, v[14:15], off
	global_load_dword v113, v[14:15], off offset:512
	global_load_dword v114, v[14:15], off offset:1024
	global_load_dword v115, v[14:15], off offset:1536
	global_load_dword v116, v[14:15], off offset:2048
	global_load_dword v117, v[14:15], off offset:2560
	global_load_dword v118, v[14:15], off offset:3072
	global_load_dword v119, v[14:15], off offset:3584
	global_load_dword v120, v[56:57], off
	global_load_dword v121, v[56:57], off offset:512
	global_load_dword v122, v[56:57], off offset:1024
	global_load_dword v123, v[56:57], off offset:1536
	global_load_dword v124, v[56:57], off offset:2048
	global_load_dword v125, v[56:57], off offset:2560
	global_load_dword v126, v[56:57], off offset:3072
	global_load_dword v127, v[56:57], off offset:3584
	global_load_dwordx4 v[64:67], v[16:17], off
	global_load_dwordx4 v[68:71], v[16:17], off offset:16
	global_load_dwordx4 v[72:75], v[16:17], off offset:32
	global_load_dwordx4 v[76:79], v[16:17], off offset:48
	v_lshl_add_u64 v[14:15], v[56:57], 0, s[100:101]
	v_lshl_add_u64 v[16:17], v[16:17], 0, 64
	s_waitcnt vmcnt(40)
	v_fmac_f32_e32 v20, v80, v128
	v_fmac_f32_e32 v20, v81, v129
	v_fmac_f32_e32 v20, v82, v130
	v_fmac_f32_e32 v20, v83, v131
	v_fmac_f32_e32 v20, v84, v132
	v_fmac_f32_e32 v20, v85, v133
	v_fmac_f32_e32 v20, v86, v134
	v_fmac_f32_e32 v20, v87, v135
	v_fmac_f32_e32 v20, v88, v136
	v_fmac_f32_e32 v20, v89, v137
	v_fmac_f32_e32 v20, v90, v138
	v_fmac_f32_e32 v20, v91, v139
	v_fmac_f32_e32 v20, v92, v140
	v_fmac_f32_e32 v20, v93, v141
	v_fmac_f32_e32 v20, v94, v142
	v_fmac_f32_e32 v20, v95, v143
	v_lshl_add_u64 v[56:57], v[14:15], 0, s[100:101]
	global_load_dword v128, v[14:15], off
	global_load_dword v129, v[14:15], off offset:512
	global_load_dword v130, v[14:15], off offset:1024
	global_load_dword v131, v[14:15], off offset:1536
	global_load_dword v132, v[14:15], off offset:2048
	global_load_dword v133, v[14:15], off offset:2560
	global_load_dword v134, v[14:15], off offset:3072
	global_load_dword v135, v[14:15], off offset:3584
	global_load_dword v136, v[56:57], off
	global_load_dword v137, v[56:57], off offset:512
	global_load_dword v138, v[56:57], off offset:1024
	global_load_dword v139, v[56:57], off offset:1536
	global_load_dword v140, v[56:57], off offset:2048
	global_load_dword v141, v[56:57], off offset:2560
	global_load_dword v142, v[56:57], off offset:3072
	global_load_dword v143, v[56:57], off offset:3584
	global_load_dwordx4 v[80:83], v[16:17], off
	global_load_dwordx4 v[84:87], v[16:17], off offset:16
	global_load_dwordx4 v[88:91], v[16:17], off offset:32
	global_load_dwordx4 v[92:95], v[16:17], off offset:48
	v_lshl_add_u64 v[14:15], v[56:57], 0, s[100:101]
	v_lshl_add_u64 v[16:17], v[16:17], 0, 64
	s_waitcnt vmcnt(40)
	v_fmac_f32_e32 v20, v96, v144
	v_fmac_f32_e32 v20, v97, v145
	v_fmac_f32_e32 v20, v98, v146
	v_fmac_f32_e32 v20, v99, v147
	v_fmac_f32_e32 v20, v100, v148
	v_fmac_f32_e32 v20, v101, v149
	v_fmac_f32_e32 v20, v102, v150
	v_fmac_f32_e32 v20, v103, v151
	v_fmac_f32_e32 v20, v104, v152
	v_fmac_f32_e32 v20, v105, v153
	v_fmac_f32_e32 v20, v106, v154
	v_fmac_f32_e32 v20, v107, v155
	v_fmac_f32_e32 v20, v108, v156
	v_fmac_f32_e32 v20, v109, v157
	v_fmac_f32_e32 v20, v110, v158
	v_fmac_f32_e32 v20, v111, v159
	v_lshl_add_u64 v[56:57], v[14:15], 0, s[100:101]
	global_load_dword v144, v[14:15], off
	global_load_dword v145, v[14:15], off offset:512
	global_load_dword v146, v[14:15], off offset:1024
	global_load_dword v147, v[14:15], off offset:1536
	global_load_dword v148, v[14:15], off offset:2048
	global_load_dword v149, v[14:15], off offset:2560
	global_load_dword v150, v[14:15], off offset:3072
	global_load_dword v151, v[14:15], off offset:3584
	global_load_dword v152, v[56:57], off
	global_load_dword v153, v[56:57], off offset:512
	global_load_dword v154, v[56:57], off offset:1024
	global_load_dword v155, v[56:57], off offset:1536
	global_load_dword v156, v[56:57], off offset:2048
	global_load_dword v157, v[56:57], off offset:2560
	global_load_dword v158, v[56:57], off offset:3072
	global_load_dword v159, v[56:57], off offset:3584
	global_load_dwordx4 v[96:99], v[16:17], off
	global_load_dwordx4 v[100:103], v[16:17], off offset:16
	global_load_dwordx4 v[104:107], v[16:17], off offset:32
	global_load_dwordx4 v[108:111], v[16:17], off offset:48
	v_lshl_add_u64 v[14:15], v[56:57], 0, s[100:101]
	v_lshl_add_u64 v[16:17], v[16:17], 0, 64
	s_waitcnt vmcnt(40)
	v_fmac_f32_e32 v20, v64, v112
	v_fmac_f32_e32 v20, v65, v113
	v_fmac_f32_e32 v20, v66, v114
	v_fmac_f32_e32 v20, v67, v115
	v_fmac_f32_e32 v20, v68, v116
	v_fmac_f32_e32 v20, v69, v117
	v_fmac_f32_e32 v20, v70, v118
	v_fmac_f32_e32 v20, v71, v119
	v_fmac_f32_e32 v20, v72, v120
	v_fmac_f32_e32 v20, v73, v121
	v_fmac_f32_e32 v20, v74, v122
	v_fmac_f32_e32 v20, v75, v123
	v_fmac_f32_e32 v20, v76, v124
	v_fmac_f32_e32 v20, v77, v125
	v_fmac_f32_e32 v20, v78, v126
	v_fmac_f32_e32 v20, v79, v127
	v_lshl_add_u64 v[56:57], v[14:15], 0, s[100:101]
	global_load_dword v112, v[14:15], off
	global_load_dword v113, v[14:15], off offset:512
	global_load_dword v114, v[14:15], off offset:1024
	global_load_dword v115, v[14:15], off offset:1536
	global_load_dword v116, v[14:15], off offset:2048
	global_load_dword v117, v[14:15], off offset:2560
	global_load_dword v118, v[14:15], off offset:3072
	global_load_dword v119, v[14:15], off offset:3584
	global_load_dword v120, v[56:57], off
	global_load_dword v121, v[56:57], off offset:512
	global_load_dword v122, v[56:57], off offset:1024
	global_load_dword v123, v[56:57], off offset:1536
	global_load_dword v124, v[56:57], off offset:2048
	global_load_dword v125, v[56:57], off offset:2560
	global_load_dword v126, v[56:57], off offset:3072
	global_load_dword v127, v[56:57], off offset:3584
	global_load_dwordx4 v[64:67], v[16:17], off
	global_load_dwordx4 v[68:71], v[16:17], off offset:16
	global_load_dwordx4 v[72:75], v[16:17], off offset:32
	global_load_dwordx4 v[76:79], v[16:17], off offset:48
	v_lshl_add_u64 v[14:15], v[56:57], 0, s[100:101]
	v_lshl_add_u64 v[16:17], v[16:17], 0, 64
	s_waitcnt vmcnt(40)
	v_fmac_f32_e32 v20, v80, v128
	v_fmac_f32_e32 v20, v81, v129
	v_fmac_f32_e32 v20, v82, v130
	v_fmac_f32_e32 v20, v83, v131
	v_fmac_f32_e32 v20, v84, v132
	v_fmac_f32_e32 v20, v85, v133
	v_fmac_f32_e32 v20, v86, v134
	v_fmac_f32_e32 v20, v87, v135
	v_fmac_f32_e32 v20, v88, v136
	v_fmac_f32_e32 v20, v89, v137
	v_fmac_f32_e32 v20, v90, v138
	v_fmac_f32_e32 v20, v91, v139
	v_fmac_f32_e32 v20, v92, v140
	v_fmac_f32_e32 v20, v93, v141
	v_fmac_f32_e32 v20, v94, v142
	v_fmac_f32_e32 v20, v95, v143
	v_lshl_add_u64 v[56:57], v[14:15], 0, s[100:101]
	global_load_dword v128, v[14:15], off
	global_load_dword v129, v[14:15], off offset:512
	global_load_dword v130, v[14:15], off offset:1024
	global_load_dword v131, v[14:15], off offset:1536
	global_load_dword v132, v[14:15], off offset:2048
	global_load_dword v133, v[14:15], off offset:2560
	global_load_dword v134, v[14:15], off offset:3072
	global_load_dword v135, v[14:15], off offset:3584
	global_load_dword v136, v[56:57], off
	global_load_dword v137, v[56:57], off offset:512
	global_load_dword v138, v[56:57], off offset:1024
	global_load_dword v139, v[56:57], off offset:1536
	global_load_dword v140, v[56:57], off offset:2048
	global_load_dword v141, v[56:57], off offset:2560
	global_load_dword v142, v[56:57], off offset:3072
	global_load_dword v143, v[56:57], off offset:3584
	global_load_dwordx4 v[80:83], v[16:17], off
	global_load_dwordx4 v[84:87], v[16:17], off offset:16
	global_load_dwordx4 v[88:91], v[16:17], off offset:32
	global_load_dwordx4 v[92:95], v[16:17], off offset:48
	v_lshl_add_u64 v[14:15], v[56:57], 0, s[100:101]
	v_lshl_add_u64 v[16:17], v[16:17], 0, 64
	s_waitcnt vmcnt(40)
	v_fmac_f32_e32 v20, v96, v144
	v_fmac_f32_e32 v20, v97, v145
	v_fmac_f32_e32 v20, v98, v146
	v_fmac_f32_e32 v20, v99, v147
	v_fmac_f32_e32 v20, v100, v148
	v_fmac_f32_e32 v20, v101, v149
	v_fmac_f32_e32 v20, v102, v150
	v_fmac_f32_e32 v20, v103, v151
	v_fmac_f32_e32 v20, v104, v152
	v_fmac_f32_e32 v20, v105, v153
	v_fmac_f32_e32 v20, v106, v154
	v_fmac_f32_e32 v20, v107, v155
	v_fmac_f32_e32 v20, v108, v156
	v_fmac_f32_e32 v20, v109, v157
	v_fmac_f32_e32 v20, v110, v158
	v_fmac_f32_e32 v20, v111, v159
	s_waitcnt vmcnt(20)
	v_fmac_f32_e32 v20, v64, v112
	v_fmac_f32_e32 v20, v65, v113
	v_fmac_f32_e32 v20, v66, v114
	v_fmac_f32_e32 v20, v67, v115
	v_fmac_f32_e32 v20, v68, v116
	v_fmac_f32_e32 v20, v69, v117
	v_fmac_f32_e32 v20, v70, v118
	v_fmac_f32_e32 v20, v71, v119
	v_fmac_f32_e32 v20, v72, v120
	v_fmac_f32_e32 v20, v73, v121
	v_fmac_f32_e32 v20, v74, v122
	v_fmac_f32_e32 v20, v75, v123
	v_fmac_f32_e32 v20, v76, v124
	v_fmac_f32_e32 v20, v77, v125
	v_fmac_f32_e32 v20, v78, v126
	v_fmac_f32_e32 v20, v79, v127
	s_waitcnt vmcnt(0)
	v_fmac_f32_e32 v20, v80, v128
	v_fmac_f32_e32 v20, v81, v129
	v_fmac_f32_e32 v20, v82, v130
	v_fmac_f32_e32 v20, v83, v131
	v_fmac_f32_e32 v20, v84, v132
	v_fmac_f32_e32 v20, v85, v133
	v_fmac_f32_e32 v20, v86, v134
	v_fmac_f32_e32 v20, v87, v135
	v_fmac_f32_e32 v20, v88, v136
	v_fmac_f32_e32 v20, v89, v137
	v_fmac_f32_e32 v20, v90, v138
	v_fmac_f32_e32 v20, v91, v139
	v_fmac_f32_e32 v20, v92, v140
	v_fmac_f32_e32 v20, v93, v141
	v_fmac_f32_e32 v20, v94, v142
	v_fmac_f32_e32 v20, v95, v143
	s_or_b64 exec, exec, s[6:7]
	ds_write_b32 v0, v20
	s_waitcnt lgkmcnt(0)
	s_barrier
	s_and_saveexec_b64 s[4:5], vcc
	s_cbranch_execz .LBB0_22
	ds_read2st64_b32 v[14:15], v0 offset1:2
	ds_read2st64_b32 v[16:17], v0 offset0:4 offset1:6
	v_lshl_add_u32 v20, s8, 7, v22
	v_ashrrev_i32_e32 v21, 31, v20
	s_waitcnt lgkmcnt(1)
	v_add_f32_e32 v14, v14, v15
	s_waitcnt lgkmcnt(0)
	v_add_f32_e32 v14, v14, v16
	v_add_f32_e32 v16, v14, v17
	v_lshl_add_u64 v[14:15], v[20:21], 2, v[6:7]
	global_store_dword v[14:15], v16, off
	s_branch .LBB0_22
